# phase X: heavier differential-attention item pairs go to the workgroups that run the (now cheaper) compress item, lighter pairs to the sliding-window workgroups
# speedup vs baseline: 1.1598x; 1.0070x over previous
; __device__ void phase_x(const Params& p, int layer, unsigned char* smem) {
;     ...
;   for (int i = blockIdx.x; i < NA / 2; i += G) {
; #pragma unroll 1
;     for (int h = 0; h < 2; ++h) {
;       int it = h ? (NA - 1 - i) : i;
;       int qt = 31 - (it >> 5); int r = it & 31; int b = r >> 2, hd = r & 3;
;       item_diff(p, layer, b, hd, qt, smem);
;     }
;   }
.LBB0_196:
	s_sub_i32 s12, 0x3ff, s9
	s_cmpk_lg_u32 s8, 0x200
	s_cbranch_scc1 .Ldiffbal_done
	s_movk_i32 s12, 0x4ff
	s_cmpk_lt_u32 s9, 0x100
	s_cselect_b32 s12, 0x2ff, s12
	s_sub_i32 s12, s12, s9
.Ldiffbal_done:
	s_mov_b64 s[18:19], -1
	s_branch .LBB0_199
